# added: prep a_f/a_b staging loads issued with the v-tile loads under one wait (was 2 serialized load->wait->LDS-write rounds)
# baseline (speedup 1.0000x reference)
; __device__ __forceinline__ float bf2f(bf16_t b) { return __uint_as_float(((unsigned)b) << 16); }
; LPHASE void phase_gla_prep(char* ws_, const float* x_, float* out_, const float* meta_, int nseq_, char* lds) {
;     ...
;     unsigned qk[16];
;     { const unsigned voff = (unsigned)(ig * 16 * 2048 + d) * 2u;
;       const char* ub = (const char*)(b2 + (size_t)row0 * 2048 + hd * 128);
; #pragma unroll
;       for (int ii = 0; ii < 16; ++ii) { const char* ubi = ub + ii * 4096;
;         qk[ii] = (unsigned)*(const bf16_t*)(ubi + voff) | ((unsigned)*(const bf16_t*)(ubi + 1024 + voff) << 16); } }
;     {
; #pragma unroll
;       for (int q = 0; q < 4; ++q) { const int c = tid + q * NTHR, i = c >> 5, c8 = (c & 31) * 8;
;         *(u32x4*)(vt + i * 264 + c8) = *(const u32x4*)(b2 + (size_t)(row0 + i) * 2048 + 1024 + hd * 256 + c8); }
;       for (int e = tid; e < 64 * 32; e += NTHR) { const int i = e >> 5, c = e & 31; af[e] = bf2f(b4[(size_t)(row0 + i) * 256 + 64 + c]); }
.LBB0_497:
	s_ashr_i32 s0, s12, 2
	s_lshl_b32 s1, s0, 8
	s_and_b32 s30, s12, 3
	s_add_i32 s1, s1, 0xffff4000
	s_lshl_b32 s12, s0, 6
	s_cmpk_gt_i32 s0, 0xff
	s_cselect_b64 s[26:27], -1, 0
	s_and_b64 s[2:3], s[26:27], exec
	s_cselect_b32 s2, s1, s12
	s_ashr_i32 s3, s2, 31
	s_lshl_b64 s[28:29], s[2:3], 12
	v_mov_b32_e32 v16, v26
	s_add_u32 s1, s24, s28
	s_addc_u32 s3, s25, s29
	v_and_b32_e32 v2, 0x7f, v16
	s_lshl_b32 s12, s30, 7
	s_lshl_b32 s28, s30, 8
	v_ashrrev_i32_e32 v49, 7, v16
	v_lshlrev_b32_e32 v0, 1, v2
	s_add_u32 s28, s1, s28
	v_lshl_or_b32 v132, v49, 16, v0
	s_addc_u32 s29, s3, 0
	v_lshl_add_u64 v[0:1], s[28:29], 0, v[132:133]
	v_add_co_u32_e32 v22, vcc, s4, v0
	s_mov_b32 s1, 0xa000
	s_nop 0
	v_addc_co_u32_e32 v23, vcc, 0, v1, vcc
	v_add_co_u32_e32 v18, vcc, s72, v0
	v_lshlrev_b32_e32 v3, 4, v16
	s_nop 0
	v_addc_co_u32_e32 v19, vcc, 0, v1, vcc
	v_add_co_u32_e32 v24, vcc, s73, v0
	v_ashrrev_i32_e32 v27, 5, v16
	s_nop 0
	v_addc_co_u32_e32 v25, vcc, 0, v1, vcc
	v_add_co_u32_e32 v20, vcc, s92, v0
	v_add_u32_e32 v17, 0x200, v16
	s_nop 0
	v_addc_co_u32_e32 v21, vcc, 0, v1, vcc
	v_add_co_u32_e32 v56, vcc, s74, v0
	v_ashrrev_i32_e32 v68, 5, v17
	s_nop 0
	v_addc_co_u32_e32 v57, vcc, 0, v1, vcc
	v_add_co_u32_e32 v4, vcc, s69, v0
	s_lshl_b32 s56, s30, 9
	s_nop 0
	v_addc_co_u32_e32 v5, vcc, 0, v1, vcc
	v_add_co_u32_e32 v60, vcc, s75, v0
	global_load_ushort v50, v132, s[28:29]
	global_load_ushort v52, v132, s[28:29] offset:1024
	global_load_ushort v47, v[18:19], off
	global_load_ushort v44, v[20:21], off offset:-4096
	global_load_ushort v51, v[20:21], off offset:1024
	global_load_ushort v43, v[4:5], off offset:-4096
	global_load_ushort v41, v[4:5], off
	global_load_ushort v53, v[4:5], off offset:1024
	v_addc_co_u32_e32 v61, vcc, 0, v1, vcc
	v_add_co_u32_e32 v4, vcc, s44, v0
	v_and_b32_e32 v132, 0x1f0, v3
	s_nop 0
	v_addc_co_u32_e32 v5, vcc, 0, v1, vcc
	v_add_co_u32_e32 v62, vcc, s5, v0
	v_add_u32_e32 v3, 0x400, v16
	s_nop 0
	v_addc_co_u32_e32 v63, vcc, 0, v1, vcc
	v_add_co_u32_e32 v6, vcc, s1, v0
	s_mov_b32 s1, 0xb000
	s_nop 0
	v_addc_co_u32_e32 v7, vcc, 0, v1, vcc
	v_add_co_u32_e32 v64, vcc, s1, v0
	s_mov_b32 s1, 0xc000
	s_nop 0
	v_addc_co_u32_e32 v65, vcc, 0, v1, vcc
	v_add_co_u32_e32 v8, vcc, s1, v0
	s_mov_b32 s1, 0xd000
	s_nop 0
	v_addc_co_u32_e32 v9, vcc, 0, v1, vcc
	v_add_co_u32_e32 v66, vcc, s1, v0
	s_mov_b32 s1, 0xe000
	s_nop 0
	v_addc_co_u32_e32 v67, vcc, 0, v1, vcc
	global_load_ushort v39, v[4:5], off offset:-4096
	global_load_ushort v38, v[4:5], off
	global_load_ushort v48, v[4:5], off offset:1024
	global_load_ushort v37, v[6:7], off offset:-4096
	global_load_ushort v35, v[6:7], off
	global_load_ushort v42, v[6:7], off offset:1024
	global_load_ushort v33, v[8:9], off offset:-4096
	global_load_ushort v32, v[8:9], off
	v_add_co_u32_e32 v4, vcc, s1, v0
	v_ashrrev_i32_e32 v69, 5, v3
	s_nop 0
	v_addc_co_u32_e32 v5, vcc, 0, v1, vcc
	global_load_ushort v36, v[8:9], off offset:1024
	global_load_ushort v31, v[4:5], off offset:-4096
	global_load_ushort v28, v[4:5], off
	global_load_ushort v29, v[4:5], off offset:1024
	v_add_u32_e32 v4, s2, v27
	v_ashrrev_i32_e32 v5, 31, v4
	v_lshlrev_b64 v[4:5], 12, v[4:5]
	v_add_u32_e32 v8, s2, v68
	v_add_u32_e32 v10, s2, v69
	s_mov_b32 s1, 0xf000
	v_lshl_add_u64 v[4:5], s[24:25], 0, v[4:5]
	v_ashrrev_i32_e32 v9, 31, v8
	v_ashrrev_i32_e32 v11, 31, v10
	v_add_co_u32_e32 v0, vcc, s1, v0
	v_lshl_add_u64 v[4:5], v[4:5], 0, s[56:57]
	v_lshlrev_b64 v[8:9], 12, v[8:9]
	v_lshlrev_b64 v[10:11], 12, v[10:11]
	v_addc_co_u32_e32 v1, vcc, 0, v1, vcc
	v_lshl_add_u64 v[4:5], v[4:5], 0, v[132:133]
	v_lshl_add_u64 v[8:9], s[24:25], 0, v[8:9]
	v_lshl_add_u64 v[10:11], s[24:25], 0, v[10:11]
	global_load_ushort v30, v[0:1], off offset:1024
	s_nop 0
	global_load_dwordx4 v[4:7], v[4:5], off offset:2048
	v_lshl_add_u64 v[8:9], v[8:9], 0, s[56:57]
	v_lshl_add_u64 v[10:11], v[10:11], 0, s[56:57]
	v_lshl_add_u64 v[8:9], v[8:9], 0, v[132:133]
	v_lshl_add_u64 v[12:13], v[10:11], 0, v[132:133]
	global_load_dwordx4 v[8:11], v[8:9], off offset:2048
	s_nop 0
	global_load_dwordx4 v[12:15], v[12:13], off offset:2048
	v_add_u32_e32 v3, 0x600, v16
	v_ashrrev_i32_e32 v70, 5, v3
	v_add_u32_e32 v54, s2, v70
	v_ashrrev_i32_e32 v55, 31, v54
	v_lshlrev_b64 v[54:55], 12, v[54:55]
	v_lshl_add_u64 v[54:55], s[24:25], 0, v[54:55]
	v_lshl_add_u64 v[54:55], v[54:55], 0, s[56:57]
	v_lshl_add_u64 v[58:59], v[54:55], 0, v[132:133]
	global_load_ushort v54, v[18:19], off offset:-4096
	global_load_ushort v55, v[18:19], off offset:1024
	global_load_ushort v45, v[20:21], off
	s_nop 0
	global_load_dwordx4 v[18:21], v[58:59], off offset:2048
	s_nop 0
	global_load_ushort v59, v[22:23], off offset:1024
	global_load_ushort v58, v[24:25], off offset:1024
	s_nop 0
	global_load_ushort v57, v[56:57], off offset:1024
	s_nop 0
	global_load_ushort v56, v[60:61], off offset:1024
	global_load_ushort v46, v[62:63], off offset:1024
	global_load_ushort v40, v[64:65], off offset:1024
	global_load_ushort v34, v[66:67], off offset:1024
	global_load_ushort v3, v[0:1], off
	v_readlane_b32 s1, v254, 31
	s_nop 1
	v_add_u32_e32 v0, s1, v132
	v_mad_u64_u32 v[22:23], s[28:29], v27, s83, v[0:1]
	s_movk_i32 s1, 0x800
	v_cmp_gt_i32_e32 vcc, s1, v16
	v_and_b32_e32 v27, 31, v16
	v_ashrrev_i32_e32 v170, 5, v16
	v_add_u32_e32 v170, s2, v170
	v_ashrrev_i32_e32 v171, 31, v170
	v_lshlrev_b64 v[170:171], 9, v[170:171]
	v_and_b32_e32 v172, 31, v16
	v_lshlrev_b32_e32 v172, 1, v172
	v_mov_b32_e32 v173, 0
	v_lshl_add_u64 v[172:173], s[36:37], 0, v[172:173]
	v_lshl_add_u64 v[170:171], v[172:173], 0, v[170:171]
	s_mov_b64 s[86:87], 0x2000
	v_lshl_add_u64 v[172:173], v[170:171], 0, s[86:87]
	v_lshl_add_u64 v[174:175], v[172:173], 0, s[86:87]
	v_lshl_add_u64 v[176:177], v[174:175], 0, s[86:87]
	global_load_ushort v178, v[170:171], off
	global_load_ushort v179, v[172:173], off
	global_load_ushort v180, v[174:175], off
	global_load_ushort v181, v[176:177], off
	s_waitcnt vmcnt(0)
	ds_write_b128 v22, v[4:7]
	v_mad_u64_u32 v[4:5], s[28:29], v68, s83, v[0:1]
	ds_write_b128 v4, v[8:11]
	v_mad_u64_u32 v[4:5], s[28:29], v69, s83, v[0:1]
	v_mad_u64_u32 v[0:1], s[28:29], v70, s83, v[0:1]
	ds_write_b128 v4, v[12:15]
	ds_write_b128 v0, v[18:21]
	v_readlane_b32 s3, v254, 32
	v_lshlrev_b32_e32 v178, 16, v178
	v_lshlrev_b32_e32 v179, 16, v179
	v_lshlrev_b32_e32 v180, 16, v180
	v_lshlrev_b32_e32 v181, 16, v181
	v_lshl_add_u32 v170, v16, 2, s3
	v_add_u32_e32 v170, 0xfffff800, v170
	ds_write_b32 v170, v178
	ds_write_b32 v170, v179 offset:2048
	ds_write_b32 v170, v180 offset:4096
	ds_write_b32 v170, v181 offset:6144
